# attention item epilogue: gate loads and output stores coalesced through a wave-private LDS transpose, gain vector staged in LDS (no serial load ladder)
# baseline (speedup 1.0000x reference)
.LBB0_227:
	v_lshlrev_b32_e32 v4, 2, v2
	global_load_dword v5, v4, s[16:17]
	global_load_dword v6, v4, s[18:19]
	global_load_dword v7, v4, s[20:21]
	global_load_dword v8, v4, s[22:23]
	s_waitcnt vmcnt(0)
	v_mul_f32_e32 v0, v5, v6
	v_mul_f32_e32 v1, v7, v8
	v_xor_b32_e32 v9, 4, v4
	ds_bpermute_b32 v10, v9, v0
	ds_bpermute_b32 v11, v9, v1
	s_waitcnt lgkmcnt(0)
	v_add_f32_e32 v0, v0, v10
	v_add_f32_e32 v1, v1, v11
	v_xor_b32_e32 v9, 8, v4
	ds_bpermute_b32 v10, v9, v0
	ds_bpermute_b32 v11, v9, v1
	s_waitcnt lgkmcnt(0)
	v_add_f32_e32 v0, v0, v10
	v_add_f32_e32 v1, v1, v11
	v_xor_b32_e32 v9, 16, v4
	ds_bpermute_b32 v10, v9, v0
	ds_bpermute_b32 v11, v9, v1
	s_waitcnt lgkmcnt(0)
	v_add_f32_e32 v0, v0, v10
	v_add_f32_e32 v1, v1, v11
	v_xor_b32_e32 v9, 32, v4
	ds_bpermute_b32 v10, v9, v0
	ds_bpermute_b32 v11, v9, v1
	s_waitcnt lgkmcnt(0)
	v_add_f32_e32 v0, v0, v10
	v_add_f32_e32 v1, v1, v11
	v_xor_b32_e32 v9, 64, v4
	ds_bpermute_b32 v10, v9, v0
	ds_bpermute_b32 v11, v9, v1
	s_waitcnt lgkmcnt(0)
	v_add_f32_e32 v0, v0, v10
	v_add_f32_e32 v1, v1, v11
	v_xor_b32_e32 v9, 128, v4
	ds_bpermute_b32 v10, v9, v0
	ds_bpermute_b32 v11, v9, v1
	s_waitcnt lgkmcnt(0)
	v_add_f32_e32 v0, v0, v10
	v_add_f32_e32 v1, v1, v11
	v_readlane_b32 s15, v255, 0
	v_readlane_b32 s0, v255, 1
	s_lshr_b32 s1, s15, 7
	s_bfe_u32 s16, s15, 0x10006
	v_add_u32_e32 v3, s0, v2
	s_lshl_b32 s0, s1, 14
	s_add_i32 s4, s0, 0
	s_add_u32 s42, s34, 0x20000
	s_addc_u32 s43, s35, 0
	s_lshl_b32 s5, s1, 5
	s_lshl_b32 s0, s16, 6
	v_and_b32_e32 v9, 63, v2
	v_writelane_b32 v255, s1, 30
	s_cmpk_lt_u32 s15, 0x80
	v_writelane_b32 v255, s0, 31
	s_cselect_b64 s[48:49], -1, 0
	s_add_i32 s0, 0, 0x1bc00
	v_lshlrev_b32_e32 v96, 3, v9
	v_lshlrev_b32_e32 v5, 1, v2
	v_lshrrev_b32_e32 v4, 1, v2
	v_add_u32_e32 v12, s0, v96
	v_readlane_b32 s0, v255, 2
	v_and_b32_e32 v6, 8, v5
	v_and_b32_e32 v4, 4, v4
	v_and_b32_e32 v11, 19, v2
	s_lshl_b32 s12, s0, 9
	s_add_i32 s0, 0, 0x11c00
	s_add_i32 s13, 0, 0x1c040
	v_or3_b32 v11, v6, v11, v4
	v_and_b32_e32 v6, 15, v2
	s_cmpk_gt_u32 s15, 0xff
	v_lshrrev_b32_e32 v7, 2, v2
	v_and_b32_e32 v8, 31, v2
	v_bfe_u32 v10, v2, 5, 1
	v_lshlrev_b32_e32 v4, 3, v6
	v_lshlrev_b32_e32 v6, 4, v6
	s_cselect_b64 s[50:51], -1, 0
	s_cmpk_lt_u32 s15, 0x100
	v_lshlrev_b32_e32 v2, 3, v2
	v_cmp_gt_u32_e64 s[18:19], 2, v9
	v_mul_f32_e32 v0, 0x3fb8aa3b, v0
	v_mul_f32_e32 v1, 0x3fb8aa3b, v1
	v_ashrrev_i32_e32 v140, 4, v3
	v_add_u32_e32 v13, s0, v6
	s_cselect_b64 s[28:29], -1, 0
	s_movk_i32 s0, 0x110
	v_and_b32_e32 v2, 24, v2
	v_writelane_b32 v255, s18, 32
	v_exp_f32_e32 v0, v0
	v_exp_f32_e32 v1, v1
	v_and_or_b32 v189, v5, 32, v2
	v_mul_lo_u32 v5, v140, s0
	s_and_b64 s[0:1], s[28:29], exec
	v_writelane_b32 v255, s19, 33
	v_cmp_gt_u32_e64 s[18:19], 4, v9
	s_cselect_b32 s0, 0, 32
	s_and_b32 s1, 64, s15
	v_writelane_b32 v255, s18, 34
	s_cmp_eq_u32 s16, 0
	s_cselect_b64 s[52:53], -1, 0
	v_writelane_b32 v255, s19, 35
	v_cmp_gt_u32_e64 s[18:19], 8, v9
	s_cmp_lg_u32 s1, 0
	v_sub_f32_e32 v0, v0, v1
	v_writelane_b32 v255, s18, 36
	v_add_u32_e32 v187, 0, v6
	v_cvt_f32_ubyte0_e32 v14, v11
	s_cselect_b64 s[66:67], -1, 0
	v_writelane_b32 v255, s19, 37
	v_cmp_gt_u32_e64 s[18:19], 16, v9
	s_add_u32 s27, s62, 0x10000000
	v_add_f32_e32 v147, 0x3e4ccccd, v0
	v_lshlrev_b32_e32 v0, 3, v10
	v_cvt_pk_bf16_f32 v14, v14, v14
	v_cmp_gt_u32_e64 s[10:11], 32, v9
	v_writelane_b32 v255, s18, 38
	s_addc_u32 s76, s63, 0
	s_add_i32 s77, s13, s0
	s_lshl_b32 s0, s89, 2
	v_add_u32_e32 v146, v187, v5
	v_mov_b32_e32 v97, 0
	v_cndmask_b32_e64 v100, 0, v14, s[10:11]
	v_mul_u32_u24_e32 v14, 0x110, v11
	v_or_b32_e32 v11, 32, v11
	v_and_or_b32 v7, v7, 3, v0
	s_movk_i32 s14, 0x140
	v_writelane_b32 v255, s19, 39
	s_add_i32 s77, s77, s0
	v_mad_u64_u32 v[148:149], s[0:1], v140, 48, v[146:147]
	v_lshlrev_b32_e32 v1, 2, v8
	v_lshlrev_b32_e32 v6, 4, v10
	v_cvt_f32_ubyte0_e32 v11, v11
	v_lshlrev_b32_e32 v2, 9, v10
	v_mad_u32_u24 v192, v7, s14, 0
	v_mov_b32_e32 v7, v97
	v_writelane_b32 v255, s16, 40
	s_lshl_b32 s0, s16, 9
	v_cmp_eq_u32_e64 s[22:23], 0, v3
	v_or_b32_e32 v186, s5, v8
	v_cmp_gt_i32_e64 s[8:9], 4, v3
	v_lshl_add_u32 v188, v3, 2, s13
	v_lshl_or_b32 v3, s16, 7, v6
	v_cvt_pk_bf16_f32 v11, v11, v11
	v_mul_lo_u32 v190, v140, s14
	v_add3_u32 v191, s4, v1, v2
	v_lshlrev_b32_e32 v2, 2, v10
	v_lshlrev_b32_e32 v214, 4, v8
	global_load_dwordx4 v[216:219], v214, s[24:25]
	v_add_u32_e32 v144, 0x20000, v6
	v_add_u32_e32 v214, 0x20000, v214
	s_waitcnt vmcnt(0)
	ds_write_b128 v214, v[216:219]
	s_waitcnt lgkmcnt(0)
	s_add_i32 s78, s0, 0
	v_sub_u32_e32 v1, v0, v8
	v_readlane_b32 s0, v255, 24
	s_mov_b32 s24, 1.0
	s_mov_b32 s41, 0
	v_ashrrev_i32_e32 v141, 31, v140
	v_cmp_eq_u32_e64 s[6:7], 0, v9
	v_mov_b32_e32 v101, v97
	v_mov_b32_e32 v102, v97
	v_mov_b32_e32 v103, v97
	v_cndmask_b32_e64 v104, 0, v11, s[10:11]
	v_mov_b32_e32 v105, v97
	v_mov_b32_e32 v106, v97
	v_mov_b32_e32 v107, v97
	v_lshl_add_u64 v[142:143], s[68:69], 0, v[96:97]
	v_add3_u32 v193, 0, v14, v3
	v_subrev_u32_e32 v149, 64, v186
	v_subrev_u32_e32 v194, s5, v1
	s_add_i32 s79, s0, -1
	s_add_i32 s72, 0, 0x1c000
	v_lshlrev_b32_e32 v150, 1, v0
	v_lshlrev_b32_e32 v152, 1, v4
	s_mov_b32 s80, 0xf800000
	v_mov_b32_e32 v195, 0x260
	v_add_u32_e32 v196, s12, v12
	v_add_u32_e32 v197, v13, v190
	s_mov_b32 s25, 0xc3200000
	v_lshlrev_b32_e32 v154, 1, v2
	v_mov_b32_e32 v198, 0x3727c5ac
	v_mbcnt_hi_u32_b32 v254, -1, v139
	v_mov_b32_e32 v199, 0x42800000
	s_mov_b32 s101, s2
	s_mov_b32 s100, 0
	s_and_b32 s101, s101, 7
	s_branch .LBB0_231

.LBB0_266:
	s_andn2_b64 vcc, exec, s[52:53]
	s_waitcnt lgkmcnt(0)
	s_barrier
	s_cbranch_vccnz .LBB0_229
	s_lshl_b32 s40, s5, 1
	v_lshl_add_u64 v[88:89], v[156:157], 0, s[40:41]
	v_mov_b32_e32 v155, v97
	v_lshl_add_u64 v[184:185], v[88:89], 0, v[154:155]
	s_movk_i32 s0, 0x1000
	v_add_co_u32_e32 v88, vcc, s0, v184
	s_mov_b64 s[0:1], 0x1800
	s_nop 0
	v_addc_co_u32_e32 v89, vcc, 0, v185, vcc
	v_readfirstlane_b32 s12, v184
	v_readfirstlane_b32 s13, v185
	v_mbcnt_lo_u32_b32 v246, -1, 0
	v_mbcnt_hi_u32_b32 v246, -1, v246
	v_and_b32_e32 v247, 31, v246
	v_lshrrev_b32_e32 v246, 5, v246
	v_lshlrev_b32_e32 v248, 3, v247
	v_lshl_add_u32 v248, v246, 13, v248
	v_readlane_b32 s14, v255, 0
	s_add_u32 s12, s12, 0x1800
	s_addc_u32 s13, s13, 0
	s_lshr_b32 s14, s14, 7
	s_mul_i32 s14, s14, 0x2400
	s_add_u32 s14, s14, 0x10000
	v_mul_u32_u24_e32 v249, 0x108, v246
	v_mul_u32_u24_e32 v250, 0x108, v247
	v_add3_u32 v249, v249, v248, s14
	v_lshl_add_u32 v250, v246, 3, v250
	v_lshlrev_b32_e32 v251, 13, v246
	v_sub_u32_e32 v249, v249, v251
	v_add_u32_e32 v250, s14, v250
	global_load_dwordx2 v[214:215], v248, s[12:13]
	s_add_u32 s12, s12, 0x4000
	s_addc_u32 s13, s13, 0
	global_load_dwordx2 v[216:217], v248, s[12:13]
	s_add_u32 s12, s12, 0x4000
	s_addc_u32 s13, s13, 0
	global_load_dwordx2 v[218:219], v248, s[12:13]
	s_add_u32 s12, s12, 0x4000
	s_addc_u32 s13, s13, 0
	global_load_dwordx2 v[220:221], v248, s[12:13]
	s_add_u32 s12, s12, 0x4000
	s_addc_u32 s13, s13, 0
	global_load_dwordx2 v[222:223], v248, s[12:13]
	s_add_u32 s12, s12, 0x4000
	s_addc_u32 s13, s13, 0
	global_load_dwordx2 v[224:225], v248, s[12:13]
	s_add_u32 s12, s12, 0x4000
	s_addc_u32 s13, s13, 0
	global_load_dwordx2 v[226:227], v248, s[12:13]
	s_add_u32 s12, s12, 0x4000
	s_addc_u32 s13, s13, 0
	global_load_dwordx2 v[228:229], v248, s[12:13]
	s_add_u32 s12, s12, 0x4000
	s_addc_u32 s13, s13, 0
	global_load_dwordx2 v[230:231], v248, s[12:13]
	s_add_u32 s12, s12, 0x4000
	s_addc_u32 s13, s13, 0
	global_load_dwordx2 v[232:233], v248, s[12:13]
	s_add_u32 s12, s12, 0x4000
	s_addc_u32 s13, s13, 0
	global_load_dwordx2 v[234:235], v248, s[12:13]
	s_add_u32 s12, s12, 0x4000
	s_addc_u32 s13, s13, 0
	global_load_dwordx2 v[236:237], v248, s[12:13]
	s_add_u32 s12, s12, 0x4000
	s_addc_u32 s13, s13, 0
	global_load_dwordx2 v[238:239], v248, s[12:13]
	s_add_u32 s12, s12, 0x4000
	s_addc_u32 s13, s13, 0
	global_load_dwordx2 v[240:241], v248, s[12:13]
	s_add_u32 s12, s12, 0x4000
	s_addc_u32 s13, s13, 0
	global_load_dwordx2 v[242:243], v248, s[12:13]
	s_add_u32 s12, s12, 0x4000
	s_addc_u32 s13, s13, 0
	global_load_dwordx2 v[244:245], v248, s[12:13]
	s_add_u32 s12, s12, 0x4000
	s_addc_u32 s13, s13, 0
	ds_read2_b32 v[164:165], v191 offset1:32
	ds_read2_b32 v[178:179], v191 offset0:64 offset1:96
	ds_read2_b32 v[162:163], v98 offset1:32
	ds_read2_b32 v[176:177], v98 offset0:64 offset1:96
	ds_read2_b32 v[160:161], v96 offset1:32
	ds_read2_b32 v[174:175], v96 offset0:64 offset1:96
	ds_read2_b32 v[158:159], v95 offset1:32
	ds_read2_b32 v[172:173], v95 offset0:64 offset1:96
	ds_read2_b32 v[156:157], v94 offset1:32
	ds_read2_b32 v[170:171], v94 offset0:64 offset1:96
	s_waitcnt vmcnt(16)
	ds_read2_b32 v[138:139], v93 offset1:32
	ds_read2_b32 v[168:169], v93 offset0:64 offset1:96
	ds_read2_b32 v[136:137], v92 offset1:32
	ds_read2_b32 v[166:167], v92 offset0:64 offset1:96
	ds_read2_b32 v[128:129], v91 offset1:32
	ds_read2_b32 v[134:135], v91 offset0:64 offset1:96
	ds_read2_b32 v[124:125], v90 offset1:32
	ds_read2_b32 v[132:133], v90 offset0:64 offset1:96
	ds_read2_b32 v[120:121], v79 offset1:32
	ds_read2_b32 v[126:127], v79 offset0:64 offset1:96
	ds_read2_b32 v[116:117], v77 offset1:32
	ds_read2_b32 v[122:123], v77 offset0:64 offset1:96
	ds_read2_b32 v[112:113], v76 offset1:32
	ds_read2_b32 v[118:119], v76 offset0:64 offset1:96
	ds_read2_b32 v[108:109], v75 offset1:32
	ds_read2_b32 v[114:115], v75 offset0:64 offset1:96
	ds_read2_b32 v[94:95], v74 offset1:32
	ds_read2_b32 v[110:111], v74 offset0:64 offset1:96
	ds_read2_b32 v[92:93], v73 offset1:32
	ds_read2_b32 v[98:99], v73 offset0:64 offset1:96
	ds_read2_b32 v[182:183], v72 offset1:32
	ds_read2_b32 v[180:181], v72 offset0:64 offset1:96
	s_waitcnt lgkmcnt(14)
	v_fma_f32 v160, v56, v78, -v160
	v_fma_f32 v161, v57, v78, -v161
	v_fma_f32 v56, v32, v78, -v156
	v_fma_f32 v57, v33, v78, -v157
	v_fma_f32 v176, v54, v78, -v176
	v_fma_f32 v177, v55, v78, -v177
	v_fma_f32 v54, v34, v78, -v170
	v_fma_f32 v55, v35, v78, -v171
	s_waitcnt lgkmcnt(1)
	v_fma_f32 v12, v12, v78, -v182
	v_fma_f32 v13, v13, v78, -v183
	s_waitcnt lgkmcnt(0)
	v_fma_f32 v14, v14, v78, -v180
	v_fma_f32 v15, v15, v78, -v181
	v_fma_f32 v178, v50, v78, -v178
	v_fma_f32 v179, v51, v78, -v179
	v_fma_f32 v164, v48, v78, -v164
	v_fma_f32 v165, v49, v78, -v165
	v_fma_f32 v162, v52, v78, -v162
	v_fma_f32 v163, v53, v78, -v163
	v_fma_f32 v58, v58, v78, -v174
	v_fma_f32 v59, v59, v78, -v175
	v_fma_f32 v62, v62, v78, -v172
	v_fma_f32 v63, v63, v78, -v173
	v_fma_f32 v60, v60, v78, -v158
	v_fma_f32 v61, v61, v78, -v159
	v_fma_f32 v50, v38, v78, -v168
	v_fma_f32 v51, v39, v78, -v169
	v_fma_f32 v52, v36, v78, -v138
	v_fma_f32 v53, v37, v78, -v139
	v_fma_f32 v42, v42, v78, -v166
	v_fma_f32 v43, v43, v78, -v167
	v_fma_f32 v48, v40, v78, -v136
	v_fma_f32 v49, v41, v78, -v137
	v_mul_f32_e32 v158, v164, v164
	v_mul_f32_e32 v159, v165, v165
	ds_read_b128 v[72:75], v144
	v_mul_f32_e32 v156, v178, v178
	v_mul_f32_e32 v157, v179, v179
	v_mul_f32_e32 v168, v162, v162
	v_mul_f32_e32 v169, v163, v163
	v_mul_f32_e32 v166, v176, v176
	v_mul_f32_e32 v167, v177, v177
	v_mul_f32_e32 v172, v160, v160
	v_mul_f32_e32 v173, v161, v161
	v_mul_f32_e32 v170, v58, v58
	v_mul_f32_e32 v171, v59, v59
	v_mul_f32_e32 v180, v60, v60
	v_mul_f32_e32 v181, v61, v61
	v_mul_f32_e32 v174, v62, v62
	v_mul_f32_e32 v175, v63, v63
	v_mul_f32_e32 v200, v56, v56
	v_mul_f32_e32 v201, v57, v57
	v_mul_f32_e32 v182, v54, v54
	v_mul_f32_e32 v183, v55, v55
	v_mul_f32_e32 v204, v52, v52
	v_mul_f32_e32 v205, v53, v53
	v_mul_f32_e32 v202, v50, v50
	v_mul_f32_e32 v203, v51, v51
	v_mul_f32_e32 v212, v48, v48
	v_mul_f32_e32 v213, v49, v49
	v_mul_f32_e32 v206, v42, v42
	v_mul_f32_e32 v207, v43, v43
	v_mul_f32_e32 v136, v12, v12
	v_mul_f32_e32 v137, v13, v13
	v_mul_f32_e32 v138, v14, v14
	v_mul_f32_e32 v139, v15, v15
	v_lshl_add_u64 v[76:77], v[184:185], 0, s[0:1]
	s_mov_b32 s0, 0x800000
	s_waitcnt vmcnt(0)
	ds_write_b64 v249, v[214:215]
	ds_write_b64 v249, v[216:217] offset:528
	ds_write_b64 v249, v[218:219] offset:1056
	ds_write_b64 v249, v[220:221] offset:1584
	ds_write_b64 v249, v[222:223] offset:2112
	ds_write_b64 v249, v[224:225] offset:2640
	ds_write_b64 v249, v[226:227] offset:3168
	ds_write_b64 v249, v[228:229] offset:3696
	ds_write_b64 v249, v[230:231] offset:4224
	ds_write_b64 v249, v[232:233] offset:4752
	ds_write_b64 v249, v[234:235] offset:5280
	ds_write_b64 v249, v[236:237] offset:5808
	ds_write_b64 v249, v[238:239] offset:6336
	ds_write_b64 v249, v[240:241] offset:6864
	ds_write_b64 v249, v[242:243] offset:7392
	ds_write_b64 v249, v[244:245] offset:7920
	s_waitcnt lgkmcnt(0)
	ds_read_b64 v[214:215], v250
	ds_read_b64 v[216:217], v250 offset:16
	ds_read_b64 v[218:219], v250 offset:240
	ds_read_b64 v[220:221], v250 offset:32
	ds_read_b64 v[222:223], v250 offset:48
	ds_read_b64 v[224:225], v250 offset:64
	ds_read_b64 v[226:227], v250 offset:80
	ds_read_b64 v[228:229], v250 offset:96
	ds_read_b64 v[230:231], v250 offset:112
	ds_read_b64 v[232:233], v250 offset:128
	ds_read_b64 v[234:235], v250 offset:144
	ds_read_b64 v[236:237], v250 offset:160
	ds_read_b64 v[238:239], v250 offset:176
	ds_read_b64 v[240:241], v250 offset:192
	ds_read_b64 v[242:243], v250 offset:208
	ds_read_b64 v[244:245], v250 offset:224
	s_waitcnt lgkmcnt(0)
	v_lshlrev_b32_e32 v208, 16, v214
	v_and_b32_e32 v209, 0xffff0000, v214
	v_lshlrev_b32_e32 v130, 16, v215
	v_mul_f32_e32 v32, 0xbfb8aa3b, v208
	v_mul_f32_e32 v33, 0xbfb8aa3b, v209
	v_mul_f32_e32 v34, 0xbfb8aa3b, v130
	v_exp_f32_e32 v32, v32
	v_exp_f32_e32 v33, v33
	v_exp_f32_e32 v79, v34
	v_and_b32_e32 v131, 0xffff0000, v215
	v_mul_f32_e32 v35, 0xbfb8aa3b, v131
	v_add_f32_e32 v32, 1.0, v32
	v_add_f32_e32 v33, 1.0, v33
	v_exp_f32_e32 v96, v35
	v_rcp_f32_e32 v210, v32
	v_rcp_f32_e32 v211, v33
	v_fma_f32 v46, v46, v78, -v134
	v_fma_f32 v47, v47, v78, -v135
	v_fma_f32 v44, v44, v78, -v128
	v_fma_f32 v45, v45, v78, -v129
	v_fma_f32 v38, v18, v78, -v132
	v_fma_f32 v39, v19, v78, -v133
	v_fma_f32 v40, v16, v78, -v124
	v_fma_f32 v41, v17, v78, -v125
	v_fma_f32 v34, v22, v78, -v126
	v_fma_f32 v35, v23, v78, -v127
	v_fma_f32 v36, v20, v78, -v120
	v_fma_f32 v37, v21, v78, -v121
	v_fma_f32 v26, v26, v78, -v122
	v_fma_f32 v27, v27, v78, -v123
	v_fma_f32 v32, v24, v78, -v116
	v_fma_f32 v33, v25, v78, -v117
	v_fma_f32 v22, v30, v78, -v118
	v_fma_f32 v23, v31, v78, -v119
	v_fma_f32 v24, v28, v78, -v112
	v_fma_f32 v25, v29, v78, -v113
	v_fma_f32 v18, v2, v78, -v114
	v_fma_f32 v19, v3, v78, -v115
	v_fma_f32 v20, v0, v78, -v108
	v_fma_f32 v21, v1, v78, -v109
	v_fma_f32 v6, v6, v78, -v110
	v_fma_f32 v7, v7, v78, -v111
	v_fma_f32 v16, v4, v78, -v94
	v_fma_f32 v17, v5, v78, -v95
	v_fma_f32 v0, v10, v78, -v98
	v_fma_f32 v1, v11, v78, -v99
	v_fma_f32 v2, v8, v78, -v92
	v_fma_f32 v3, v9, v78, -v93
	v_add_f32_e32 v78, v158, v159
	v_add_f32_e32 v78, v78, v156
	v_add_f32_e32 v78, v78, v157
	v_add_f32_e32 v78, v78, v168
	v_add_f32_e32 v78, v78, v169
	v_add_f32_e32 v78, v78, v166
	v_add_f32_e32 v78, v78, v167
	v_add_f32_e32 v78, v78, v172
	v_add_f32_e32 v78, v78, v173
	v_add_f32_e32 v78, v78, v170
	v_add_f32_e32 v78, v78, v171
	v_add_f32_e32 v78, v78, v180
	v_add_f32_e32 v78, v78, v181
	v_add_f32_e32 v78, v78, v174
	v_add_f32_e32 v78, v78, v175
	v_add_f32_e32 v78, v78, v200
	v_add_f32_e32 v78, v78, v201
	v_add_f32_e32 v78, v78, v182
	v_add_f32_e32 v78, v78, v183
	v_add_f32_e32 v78, v78, v204
	v_add_f32_e32 v78, v78, v205
	v_add_f32_e32 v78, v78, v202
	v_add_f32_e32 v78, v78, v203
	v_add_f32_e32 v78, v78, v212
	v_add_f32_e32 v78, v78, v213
	v_add_f32_e32 v78, v78, v206
	v_mul_f32_e32 v128, v44, v44
	v_mul_f32_e32 v129, v45, v45
	v_add_f32_e32 v78, v78, v207
	v_add_f32_e32 v78, v78, v128
	v_mul_f32_e32 v134, v46, v46
	v_mul_f32_e32 v135, v47, v47
	v_add_f32_e32 v78, v78, v129
	v_add_f32_e32 v78, v78, v134
	v_mul_f32_e32 v124, v40, v40
	v_mul_f32_e32 v125, v41, v41
	v_add_f32_e32 v78, v78, v135
	v_add_f32_e32 v78, v78, v124
	v_mul_f32_e32 v132, v38, v38
	v_mul_f32_e32 v133, v39, v39
	v_add_f32_e32 v78, v78, v125
	v_add_f32_e32 v78, v78, v132
	v_mul_f32_e32 v120, v36, v36
	v_mul_f32_e32 v121, v37, v37
	v_add_f32_e32 v78, v78, v133
	v_add_f32_e32 v78, v78, v120
	v_mul_f32_e32 v126, v34, v34
	v_mul_f32_e32 v127, v35, v35
	v_add_f32_e32 v78, v78, v121
	v_add_f32_e32 v78, v78, v126
	v_mul_f32_e32 v116, v32, v32
	v_mul_f32_e32 v117, v33, v33
	v_add_f32_e32 v78, v78, v127
	v_add_f32_e32 v78, v78, v116
	v_mul_f32_e32 v122, v26, v26
	v_mul_f32_e32 v123, v27, v27
	v_add_f32_e32 v78, v78, v117
	v_add_f32_e32 v78, v78, v122
	v_mul_f32_e32 v28, v24, v24
	v_mul_f32_e32 v29, v25, v25
	v_add_f32_e32 v78, v78, v123
	v_add_f32_e32 v28, v78, v28
	v_mul_f32_e32 v30, v22, v22
	v_mul_f32_e32 v31, v23, v23
	v_add_f32_e32 v28, v28, v29
	v_add_f32_e32 v28, v28, v30
	v_mul_f32_e32 v108, v20, v20
	v_mul_f32_e32 v109, v21, v21
	v_add_f32_e32 v28, v28, v31
	v_add_f32_e32 v28, v28, v108
	v_mul_f32_e32 v112, v18, v18
	v_mul_f32_e32 v113, v19, v19
	v_add_f32_e32 v28, v28, v109
	v_add_f32_e32 v28, v28, v112
	v_mul_f32_e32 v4, v16, v16
	v_mul_f32_e32 v5, v17, v17
	v_add_f32_e32 v28, v28, v113
	v_add_f32_e32 v4, v28, v4
	v_mul_f32_e32 v110, v6, v6
	v_mul_f32_e32 v111, v7, v7
	v_add_f32_e32 v4, v4, v5
	v_add_f32_e32 v4, v4, v110
	v_mul_f32_e32 v8, v2, v2
	v_mul_f32_e32 v9, v3, v3
	v_add_f32_e32 v4, v4, v111
	v_add_f32_e32 v4, v4, v8
	v_mul_f32_e32 v10, v0, v0
	v_mul_f32_e32 v11, v1, v1
	v_add_f32_e32 v4, v4, v9
	v_add_f32_e32 v4, v4, v10
	v_add_f32_e32 v4, v4, v11
	v_add_f32_e32 v4, v4, v136
	v_add_f32_e32 v4, v4, v137
	v_add_f32_e32 v4, v4, v138
	v_add_f32_e32 v8, v4, v139
	ds_bpermute_b32 v9, v151, v8
	v_add_f32_e32 v4, 1.0, v79
	v_add_f32_e32 v5, 1.0, v96
	v_rcp_f32_e32 v4, v4
	v_rcp_f32_e32 v5, v5
	s_waitcnt lgkmcnt(0)
	v_add_f32_e32 v8, v8, v9
	v_fmamk_f32 v8, v8, 0x3c000000, v198
	v_mul_f32_e32 v9, 0x4b800000, v8
	v_cmp_gt_f32_e32 vcc, s0, v8
	v_mul_f32_e32 v10, v4, v130
	v_mul_f32_e32 v11, v5, v131
	s_nop 0
	v_cndmask_b32_e32 v8, v8, v9, vcc
	v_rsq_f32_e32 v28, v8
	v_mul_f32_e32 v8, v210, v208
	v_mul_f32_e32 v9, v211, v209
	v_mul_f32_e32 v4, 0x45800000, v28
	v_cndmask_b32_e32 v4, v28, v4, vcc
	v_mul_f32_e32 v4, 0x3f4ccccd, v4
	v_mul_f32_e32 v28, v164, v4
	v_mul_f32_e32 v29, v165, v4
	v_mul_f32_e32 v28, v72, v28
	v_mul_f32_e32 v29, v73, v29
	s_nop 0
	v_mul_f32_e32 v8, v8, v28
	v_mul_f32_e32 v9, v9, v29
	v_mul_f32_e32 v28, v178, v4
	v_mul_f32_e32 v29, v179, v4
	v_cvt_pk_bf16_f32 v8, v8, v9
	v_mul_f32_e32 v28, v74, v28
	v_mul_f32_e32 v29, v75, v29
	v_lshlrev_b32_e32 v74, 16, v216
	v_mul_f32_e32 v10, v10, v28
	v_mul_f32_e32 v11, v11, v29
	v_and_b32_e32 v75, 0xffff0000, v216
	v_cvt_pk_bf16_f32 v9, v10, v11
	ds_write_b64 v250, v[8:9]
	ds_read_b128 v[8:11], v144 offset:32
	s_nop 0
	v_mul_f32_e32 v5, 0xbfb8aa3b, v74
	v_exp_f32_e32 v5, v5
	v_mul_f32_e32 v78, 0xbfb8aa3b, v75
	v_exp_f32_e32 v79, v78
	v_lshlrev_b32_e32 v88, 16, v217
	v_add_f32_e32 v5, 1.0, v5
	v_rcp_f32_e32 v78, v5
	v_add_f32_e32 v5, 1.0, v79
	v_and_b32_e32 v89, 0xffff0000, v217
	v_mul_f32_e32 v79, 0xbfb8aa3b, v88
	v_exp_f32_e32 v90, v79
	v_mul_f32_e32 v79, 0xbfb8aa3b, v89
	v_exp_f32_e32 v91, v79
	v_rcp_f32_e32 v79, v5
	v_add_f32_e32 v5, 1.0, v90
	v_rcp_f32_e32 v90, v5
	v_add_f32_e32 v5, 1.0, v91
	v_rcp_f32_e32 v91, v5
	v_mul_f32_e32 v74, v78, v74
	v_mul_f32_e32 v75, v79, v75
	v_mul_f32_e32 v78, v90, v88
	v_mul_f32_e32 v79, v91, v89
	v_mul_f32_e32 v88, v162, v4
	v_mul_f32_e32 v89, v163, v4
	s_waitcnt lgkmcnt(0)
	v_mul_f32_e32 v8, v8, v88
	v_mul_f32_e32 v9, v9, v89
	s_nop 0
	v_mul_f32_e32 v8, v74, v8
	v_mul_f32_e32 v9, v75, v9
	v_mul_f32_e32 v74, v176, v4
	v_mul_f32_e32 v75, v177, v4
	v_cvt_pk_bf16_f32 v8, v8, v9
	v_mul_f32_e32 v10, v10, v74
	v_mul_f32_e32 v11, v11, v75
	v_lshlrev_b32_e32 v74, 16, v220
	v_mul_f32_e32 v10, v78, v10
	v_mul_f32_e32 v11, v79, v11
	v_and_b32_e32 v75, 0xffff0000, v220
	v_cvt_pk_bf16_f32 v9, v10, v11
	ds_write_b64 v250, v[8:9] offset:16
	ds_read_b128 v[8:11], v144 offset:64
	v_mul_f32_e32 v5, 0xbfb8aa3b, v74
	v_exp_f32_e32 v5, v5
	v_mul_f32_e32 v28, 0xbfb8aa3b, v75
	v_exp_f32_e32 v78, v28
	v_and_b32_e32 v79, 0xffff0000, v221
	v_add_f32_e32 v5, 1.0, v5
	v_rcp_f32_e32 v28, v5
	v_add_f32_e32 v5, 1.0, v78
	v_lshlrev_b32_e32 v78, 16, v221
	v_mul_f32_e32 v29, 0xbfb8aa3b, v78
	v_exp_f32_e32 v88, v29
	v_mul_f32_e32 v29, 0xbfb8aa3b, v79
	v_exp_f32_e32 v89, v29
	v_rcp_f32_e32 v29, v5
	v_add_f32_e32 v5, 1.0, v88
	v_rcp_f32_e32 v88, v5
	v_add_f32_e32 v5, 1.0, v89
	v_rcp_f32_e32 v89, v5
	v_mul_f32_e32 v28, v28, v74
	v_mul_f32_e32 v29, v29, v75
	v_mul_f32_e32 v74, v88, v78
	v_mul_f32_e32 v75, v89, v79
	v_mul_f32_e32 v78, v160, v4
	v_mul_f32_e32 v79, v161, v4
	s_waitcnt lgkmcnt(0)
	v_mul_f32_e32 v8, v8, v78
	v_mul_f32_e32 v9, v9, v79
	s_nop 0
	v_mul_f32_e32 v8, v8, v28
	v_mul_f32_e32 v9, v9, v29
	v_mul_f32_e32 v28, v58, v4
	v_mul_f32_e32 v29, v59, v4
	v_cvt_pk_bf16_f32 v8, v8, v9
	v_mul_f32_e32 v10, v10, v28
	v_mul_f32_e32 v11, v11, v29
	v_lshlrev_b32_e32 v28, 16, v222
	v_mul_f32_e32 v10, v10, v74
	v_mul_f32_e32 v11, v11, v75
	v_and_b32_e32 v29, 0xffff0000, v222
	v_cvt_pk_bf16_f32 v9, v10, v11
	ds_write_b64 v250, v[8:9] offset:32
	ds_read_b128 v[8:11], v144 offset:96
	v_lshlrev_b32_e32 v30, 16, v223
	v_and_b32_e32 v31, 0xffff0000, v223
	v_mul_f32_e32 v5, 0xbfb8aa3b, v28
	v_mul_f32_e32 v58, 0xbfb8aa3b, v29
	v_mul_f32_e32 v59, 0xbfb8aa3b, v30
	v_mul_f32_e32 v74, 0xbfb8aa3b, v31
	v_exp_f32_e32 v5, v5
	v_exp_f32_e32 v58, v58
	v_exp_f32_e32 v59, v59
	v_exp_f32_e32 v74, v74
	v_add_f32_e32 v5, 1.0, v5
	v_add_f32_e32 v75, 1.0, v58
	v_add_f32_e32 v78, 1.0, v59
	v_add_f32_e32 v79, 1.0, v74
	v_rcp_f32_e32 v58, v5
	v_rcp_f32_e32 v59, v75
	v_rcp_f32_e32 v74, v78
	v_rcp_f32_e32 v75, v79
	v_mul_f32_e32 v60, v60, v4
	v_mul_f32_e32 v61, v61, v4
	v_mul_f32_e32 v62, v62, v4
	v_mul_f32_e32 v63, v63, v4
	v_mul_f32_e32 v28, v58, v28
	v_mul_f32_e32 v29, v59, v29
	v_mul_f32_e32 v30, v74, v30
	v_mul_f32_e32 v31, v75, v31
	v_lshlrev_b32_e32 v58, 16, v225
	v_and_b32_e32 v59, 0xffff0000, v225
	s_waitcnt lgkmcnt(0)
	v_mul_f32_e32 v8, v8, v60
	v_mul_f32_e32 v9, v9, v61
	v_mul_f32_e32 v10, v10, v62
	v_mul_f32_e32 v11, v11, v63
	v_mul_f32_e32 v8, v8, v28
	v_mul_f32_e32 v9, v9, v29
	v_mul_f32_e32 v10, v10, v30
	v_mul_f32_e32 v11, v11, v31
	v_cvt_pk_bf16_f32 v8, v8, v9
	v_cvt_pk_bf16_f32 v9, v10, v11
	ds_write_b64 v250, v[8:9] offset:48
	ds_read_b128 v[8:11], v144 offset:128
	s_nop 0
	v_lshlrev_b32_e32 v30, 16, v224
	v_and_b32_e32 v31, 0xffff0000, v224
	v_mul_f32_e32 v5, 0xbfb8aa3b, v30
	v_mul_f32_e32 v60, 0xbfb8aa3b, v31
	v_mul_f32_e32 v61, 0xbfb8aa3b, v58
	v_mul_f32_e32 v62, 0xbfb8aa3b, v59
	v_exp_f32_e32 v5, v5
	v_exp_f32_e32 v60, v60
	v_exp_f32_e32 v61, v61
	v_exp_f32_e32 v62, v62
	v_add_f32_e32 v5, 1.0, v5
	v_add_f32_e32 v63, 1.0, v60
	v_add_f32_e32 v72, 1.0, v61
	v_add_f32_e32 v73, 1.0, v62
	v_rcp_f32_e32 v60, v5
	v_rcp_f32_e32 v61, v63
	v_rcp_f32_e32 v62, v72
	v_rcp_f32_e32 v63, v73
	v_mul_f32_e32 v56, v56, v4
	v_mul_f32_e32 v57, v57, v4
	v_mul_f32_e32 v54, v54, v4
	v_mul_f32_e32 v55, v55, v4
	v_mul_f32_e32 v30, v60, v30
	v_mul_f32_e32 v31, v61, v31
	v_mul_f32_e32 v58, v62, v58
	v_mul_f32_e32 v59, v63, v59
	s_waitcnt lgkmcnt(0)
	v_mul_f32_e32 v8, v56, v8
	v_mul_f32_e32 v9, v57, v9
	v_mul_f32_e32 v10, v54, v10
	v_mul_f32_e32 v11, v55, v11
	v_mul_f32_e32 v8, v8, v30
	v_mul_f32_e32 v9, v9, v31
	v_mul_f32_e32 v10, v10, v58
	v_mul_f32_e32 v11, v11, v59
	v_cvt_pk_bf16_f32 v8, v8, v9
	v_cvt_pk_bf16_f32 v9, v10, v11
	ds_write_b64 v250, v[8:9] offset:64
	ds_read_b128 v[8:11], v144 offset:160
	s_nop 0
	v_lshlrev_b32_e32 v58, 16, v226
	v_and_b32_e32 v59, 0xffff0000, v226
	v_lshlrev_b32_e32 v28, 16, v227
	v_and_b32_e32 v29, 0xffff0000, v227
	v_mul_f32_e32 v5, 0xbfb8aa3b, v58
	v_mul_f32_e32 v60, 0xbfb8aa3b, v59
	v_mul_f32_e32 v61, 0xbfb8aa3b, v28
	v_mul_f32_e32 v62, 0xbfb8aa3b, v29
	v_exp_f32_e32 v5, v5
	v_exp_f32_e32 v60, v60
	v_exp_f32_e32 v61, v61
	v_exp_f32_e32 v62, v62
	v_add_f32_e32 v5, 1.0, v5
	v_add_f32_e32 v63, 1.0, v60
	v_add_f32_e32 v72, 1.0, v61
	v_add_f32_e32 v73, 1.0, v62
	v_rcp_f32_e32 v60, v5
	v_rcp_f32_e32 v61, v63
	v_rcp_f32_e32 v62, v72
	v_rcp_f32_e32 v63, v73
	v_mul_f32_e32 v52, v52, v4
	v_mul_f32_e32 v53, v53, v4
	v_mul_f32_e32 v50, v50, v4
	v_mul_f32_e32 v51, v51, v4
	v_mul_f32_e32 v58, v60, v58
	v_mul_f32_e32 v59, v61, v59
	v_mul_f32_e32 v28, v62, v28
	v_mul_f32_e32 v29, v63, v29
	s_waitcnt lgkmcnt(0)
	v_mul_f32_e32 v8, v52, v8
	v_mul_f32_e32 v9, v53, v9
	v_mul_f32_e32 v10, v50, v10
	v_mul_f32_e32 v11, v51, v11
	v_mul_f32_e32 v8, v8, v58
	v_mul_f32_e32 v9, v9, v59
	v_mul_f32_e32 v10, v10, v28
	v_mul_f32_e32 v11, v11, v29
	v_cvt_pk_bf16_f32 v8, v8, v9
	v_cvt_pk_bf16_f32 v9, v10, v11
	ds_write_b64 v250, v[8:9] offset:80
	ds_read_b128 v[8:11], v144 offset:192
	v_lshlrev_b32_e32 v28, 16, v228
	v_and_b32_e32 v29, 0xffff0000, v228
	v_lshlrev_b32_e32 v30, 16, v229
	v_and_b32_e32 v31, 0xffff0000, v229
	v_mul_f32_e32 v5, 0xbfb8aa3b, v28
	v_mul_f32_e32 v50, 0xbfb8aa3b, v29
	v_mul_f32_e32 v51, 0xbfb8aa3b, v30
	v_mul_f32_e32 v52, 0xbfb8aa3b, v31
	v_exp_f32_e32 v5, v5
	v_exp_f32_e32 v50, v50
	v_exp_f32_e32 v51, v51
	v_exp_f32_e32 v52, v52
	v_add_f32_e32 v5, 1.0, v5
	v_add_f32_e32 v53, 1.0, v50
	v_add_f32_e32 v58, 1.0, v51
	v_add_f32_e32 v59, 1.0, v52
	v_rcp_f32_e32 v50, v5
	v_rcp_f32_e32 v51, v53
	v_rcp_f32_e32 v52, v58
	v_rcp_f32_e32 v53, v59
	v_mul_f32_e32 v48, v48, v4
	v_mul_f32_e32 v49, v49, v4
	v_mul_f32_e32 v42, v42, v4
	v_mul_f32_e32 v43, v43, v4
	v_mul_f32_e32 v28, v50, v28
	v_mul_f32_e32 v29, v51, v29
	v_mul_f32_e32 v30, v52, v30
	v_mul_f32_e32 v31, v53, v31
	s_waitcnt lgkmcnt(0)
	v_mul_f32_e32 v8, v48, v8
	v_mul_f32_e32 v9, v49, v9
	v_mul_f32_e32 v10, v42, v10
	v_mul_f32_e32 v11, v43, v11
	v_mul_f32_e32 v8, v8, v28
	v_mul_f32_e32 v9, v9, v29
	v_mul_f32_e32 v10, v10, v30
	v_mul_f32_e32 v11, v11, v31
	v_cvt_pk_bf16_f32 v8, v8, v9
	v_cvt_pk_bf16_f32 v9, v10, v11
	ds_write_b64 v250, v[8:9] offset:96
	ds_read_b128 v[8:11], v144 offset:224
	v_lshlrev_b32_e32 v28, 16, v230
	v_and_b32_e32 v29, 0xffff0000, v230
	v_lshlrev_b32_e32 v30, 16, v231
	v_and_b32_e32 v31, 0xffff0000, v231
	v_mul_f32_e32 v5, 0xbfb8aa3b, v28
	v_mul_f32_e32 v42, 0xbfb8aa3b, v29
	v_mul_f32_e32 v43, 0xbfb8aa3b, v30
	v_mul_f32_e32 v48, 0xbfb8aa3b, v31
	v_exp_f32_e32 v5, v5
	v_exp_f32_e32 v42, v42
	v_exp_f32_e32 v43, v43
	v_exp_f32_e32 v48, v48
	v_add_f32_e32 v5, 1.0, v5
	v_add_f32_e32 v49, 1.0, v42
	v_add_f32_e32 v50, 1.0, v43
	v_add_f32_e32 v51, 1.0, v48
	v_rcp_f32_e32 v42, v5
	v_rcp_f32_e32 v43, v49
	v_rcp_f32_e32 v48, v50
	v_rcp_f32_e32 v49, v51
	v_mul_f32_e32 v44, v44, v4
	v_mul_f32_e32 v45, v45, v4
	v_mul_f32_e32 v46, v46, v4
	v_mul_f32_e32 v47, v47, v4
	v_mul_f32_e32 v28, v42, v28
	v_mul_f32_e32 v29, v43, v29
	v_mul_f32_e32 v30, v48, v30
	v_mul_f32_e32 v31, v49, v31
	v_lshlrev_b32_e32 v42, 16, v233
	v_and_b32_e32 v43, 0xffff0000, v233
	s_waitcnt lgkmcnt(0)
	v_mul_f32_e32 v8, v44, v8
	v_mul_f32_e32 v9, v45, v9
	v_mul_f32_e32 v10, v46, v10
	v_mul_f32_e32 v11, v47, v11
	v_mul_f32_e32 v8, v8, v28
	v_mul_f32_e32 v9, v9, v29
	v_mul_f32_e32 v10, v10, v30
	v_mul_f32_e32 v11, v11, v31
	v_cvt_pk_bf16_f32 v8, v8, v9
	v_cvt_pk_bf16_f32 v9, v10, v11
	ds_write_b64 v250, v[8:9] offset:112
	ds_read_b128 v[8:11], v144 offset:256
	s_nop 0
	v_lshlrev_b32_e32 v30, 16, v232
	v_and_b32_e32 v31, 0xffff0000, v232
	v_mul_f32_e32 v5, 0xbfb8aa3b, v30
	v_mul_f32_e32 v44, 0xbfb8aa3b, v31
	v_mul_f32_e32 v45, 0xbfb8aa3b, v42
	v_mul_f32_e32 v46, 0xbfb8aa3b, v43
	v_exp_f32_e32 v5, v5
	v_exp_f32_e32 v44, v44
	v_exp_f32_e32 v45, v45
	v_exp_f32_e32 v46, v46
	v_add_f32_e32 v5, 1.0, v5
	v_add_f32_e32 v47, 1.0, v44
	v_add_f32_e32 v48, 1.0, v45
	v_add_f32_e32 v49, 1.0, v46
	v_rcp_f32_e32 v44, v5
	v_rcp_f32_e32 v45, v47
	v_rcp_f32_e32 v46, v48
	v_rcp_f32_e32 v47, v49
	v_mul_f32_e32 v40, v40, v4
	v_mul_f32_e32 v41, v41, v4
	v_mul_f32_e32 v38, v38, v4
	v_mul_f32_e32 v39, v39, v4
	v_mul_f32_e32 v30, v44, v30
	v_mul_f32_e32 v31, v45, v31
	v_mul_f32_e32 v42, v46, v42
	v_mul_f32_e32 v43, v47, v43
	s_waitcnt lgkmcnt(0)
	v_mul_f32_e32 v8, v40, v8
	v_mul_f32_e32 v9, v41, v9
	v_mul_f32_e32 v10, v38, v10
	v_mul_f32_e32 v11, v39, v11
	v_mul_f32_e32 v8, v8, v30
	v_mul_f32_e32 v9, v9, v31
	v_mul_f32_e32 v10, v10, v42
	v_mul_f32_e32 v11, v11, v43
	v_cvt_pk_bf16_f32 v8, v8, v9
	v_cvt_pk_bf16_f32 v9, v10, v11
	ds_write_b64 v250, v[8:9] offset:128
	ds_read_b128 v[8:11], v144 offset:288
	s_nop 0
	v_lshlrev_b32_e32 v42, 16, v234
	v_and_b32_e32 v43, 0xffff0000, v234
	v_lshlrev_b32_e32 v28, 16, v235
	v_and_b32_e32 v29, 0xffff0000, v235
	v_mul_f32_e32 v5, 0xbfb8aa3b, v42
	v_mul_f32_e32 v44, 0xbfb8aa3b, v43
	v_mul_f32_e32 v45, 0xbfb8aa3b, v28
	v_mul_f32_e32 v46, 0xbfb8aa3b, v29
	v_exp_f32_e32 v5, v5
	v_exp_f32_e32 v44, v44
	v_exp_f32_e32 v45, v45
	v_exp_f32_e32 v46, v46
	v_add_f32_e32 v5, 1.0, v5
	v_add_f32_e32 v47, 1.0, v44
	v_add_f32_e32 v48, 1.0, v45
	v_add_f32_e32 v49, 1.0, v46
	v_rcp_f32_e32 v44, v5
	v_rcp_f32_e32 v45, v47
	v_rcp_f32_e32 v46, v48
	v_rcp_f32_e32 v47, v49
	v_mul_f32_e32 v36, v36, v4
	v_mul_f32_e32 v37, v37, v4
	v_mul_f32_e32 v34, v34, v4
	v_mul_f32_e32 v35, v35, v4
	v_mul_f32_e32 v42, v44, v42
	v_mul_f32_e32 v43, v45, v43
	v_mul_f32_e32 v28, v46, v28
	v_mul_f32_e32 v29, v47, v29
	s_waitcnt lgkmcnt(0)
	v_mul_f32_e32 v8, v36, v8
	v_mul_f32_e32 v9, v37, v9
	v_mul_f32_e32 v10, v34, v10
	v_mul_f32_e32 v11, v35, v11
	v_mul_f32_e32 v8, v8, v42
	v_mul_f32_e32 v9, v9, v43
	v_mul_f32_e32 v10, v10, v28
	v_mul_f32_e32 v11, v11, v29
	v_cvt_pk_bf16_f32 v8, v8, v9
	v_cvt_pk_bf16_f32 v9, v10, v11
	ds_write_b64 v250, v[8:9] offset:144
	ds_read_b128 v[8:11], v144 offset:320
	v_lshlrev_b32_e32 v28, 16, v236
	v_and_b32_e32 v29, 0xffff0000, v236
	v_lshlrev_b32_e32 v30, 16, v237
	v_and_b32_e32 v31, 0xffff0000, v237
	v_mul_f32_e32 v5, 0xbfb8aa3b, v28
	v_mul_f32_e32 v34, 0xbfb8aa3b, v29
	v_mul_f32_e32 v35, 0xbfb8aa3b, v30
	v_mul_f32_e32 v36, 0xbfb8aa3b, v31
	v_exp_f32_e32 v5, v5
	v_exp_f32_e32 v34, v34
	v_exp_f32_e32 v35, v35
	v_exp_f32_e32 v36, v36
	v_add_f32_e32 v5, 1.0, v5
	v_add_f32_e32 v37, 1.0, v34
	v_add_f32_e32 v42, 1.0, v35
	v_add_f32_e32 v43, 1.0, v36
	v_rcp_f32_e32 v34, v5
	v_rcp_f32_e32 v35, v37
	v_rcp_f32_e32 v36, v42
	v_rcp_f32_e32 v37, v43
	v_mul_f32_e32 v32, v32, v4
	v_mul_f32_e32 v33, v33, v4
	v_mul_f32_e32 v26, v26, v4
	v_mul_f32_e32 v27, v27, v4
	v_mul_f32_e32 v28, v34, v28
	v_mul_f32_e32 v29, v35, v29
	v_mul_f32_e32 v30, v36, v30
	v_mul_f32_e32 v31, v37, v31
	s_waitcnt lgkmcnt(0)
	v_mul_f32_e32 v8, v32, v8
	v_mul_f32_e32 v9, v33, v9
	v_mul_f32_e32 v10, v26, v10
	v_mul_f32_e32 v11, v27, v11
	v_mul_f32_e32 v8, v8, v28
	v_mul_f32_e32 v9, v9, v29
	v_mul_f32_e32 v10, v10, v30
	v_mul_f32_e32 v11, v11, v31
	v_cvt_pk_bf16_f32 v8, v8, v9
	v_cvt_pk_bf16_f32 v9, v10, v11
	ds_write_b64 v250, v[8:9] offset:160
	ds_read_b128 v[8:11], v144 offset:352
	v_lshlrev_b32_e32 v26, 16, v238
	v_and_b32_e32 v27, 0xffff0000, v238
	v_lshlrev_b32_e32 v28, 16, v239
	v_and_b32_e32 v29, 0xffff0000, v239
	v_mul_f32_e32 v5, 0xbfb8aa3b, v26
	v_mul_f32_e32 v30, 0xbfb8aa3b, v27
	v_mul_f32_e32 v31, 0xbfb8aa3b, v28
	v_mul_f32_e32 v32, 0xbfb8aa3b, v29
	v_exp_f32_e32 v5, v5
	v_exp_f32_e32 v30, v30
	v_exp_f32_e32 v31, v31
	v_exp_f32_e32 v32, v32
	v_add_f32_e32 v5, 1.0, v5
	v_add_f32_e32 v33, 1.0, v30
	v_add_f32_e32 v34, 1.0, v31
	v_add_f32_e32 v35, 1.0, v32
	v_rcp_f32_e32 v30, v5
	v_rcp_f32_e32 v31, v33
	v_rcp_f32_e32 v32, v34
	v_rcp_f32_e32 v33, v35
	v_mul_f32_e32 v24, v24, v4
	v_mul_f32_e32 v25, v25, v4
	v_mul_f32_e32 v22, v22, v4
	v_mul_f32_e32 v23, v23, v4
	v_mul_f32_e32 v26, v30, v26
	v_mul_f32_e32 v27, v31, v27
	v_mul_f32_e32 v28, v32, v28
	v_mul_f32_e32 v29, v33, v29
	s_waitcnt lgkmcnt(0)
	v_mul_f32_e32 v8, v24, v8
	v_mul_f32_e32 v9, v25, v9
	v_mul_f32_e32 v10, v22, v10
	v_mul_f32_e32 v11, v23, v11
	v_mul_f32_e32 v8, v8, v26
	v_mul_f32_e32 v9, v9, v27
	v_mul_f32_e32 v10, v10, v28
	v_mul_f32_e32 v11, v11, v29
	v_cvt_pk_bf16_f32 v8, v8, v9
	v_cvt_pk_bf16_f32 v9, v10, v11
	ds_write_b64 v250, v[8:9] offset:176
	ds_read_b128 v[8:11], v144 offset:384
	s_nop 0
	v_lshlrev_b32_e32 v24, 16, v240
	v_and_b32_e32 v25, 0xffff0000, v240
	v_lshlrev_b32_e32 v26, 16, v241
	v_and_b32_e32 v27, 0xffff0000, v241
	v_mul_f32_e32 v5, 0xbfb8aa3b, v24
	v_mul_f32_e32 v28, 0xbfb8aa3b, v25
	v_mul_f32_e32 v29, 0xbfb8aa3b, v26
	v_mul_f32_e32 v30, 0xbfb8aa3b, v27
	v_exp_f32_e32 v5, v5
	v_exp_f32_e32 v28, v28
	v_exp_f32_e32 v29, v29
	v_exp_f32_e32 v30, v30
	v_add_f32_e32 v5, 1.0, v5
	v_add_f32_e32 v31, 1.0, v28
	v_add_f32_e32 v32, 1.0, v29
	v_add_f32_e32 v33, 1.0, v30
	v_rcp_f32_e32 v28, v5
	v_rcp_f32_e32 v29, v31
	v_rcp_f32_e32 v30, v32
	v_rcp_f32_e32 v31, v33
	v_mul_f32_e32 v20, v20, v4
	v_mul_f32_e32 v21, v21, v4
	v_mul_f32_e32 v18, v18, v4
	v_mul_f32_e32 v19, v19, v4
	v_mul_f32_e32 v24, v28, v24
	v_mul_f32_e32 v25, v29, v25
	v_mul_f32_e32 v26, v30, v26
	v_mul_f32_e32 v27, v31, v27
	s_waitcnt lgkmcnt(0)
	v_mul_f32_e32 v8, v20, v8
	v_mul_f32_e32 v9, v21, v9
	v_mul_f32_e32 v10, v18, v10
	v_mul_f32_e32 v11, v19, v11
	v_mul_f32_e32 v8, v8, v24
	v_mul_f32_e32 v9, v9, v25
	v_mul_f32_e32 v10, v10, v26
	v_mul_f32_e32 v11, v11, v27
	v_cvt_pk_bf16_f32 v8, v8, v9
	v_cvt_pk_bf16_f32 v9, v10, v11
	ds_write_b64 v250, v[8:9] offset:192
	ds_read_b128 v[8:11], v144 offset:416
	s_nop 0
	v_lshlrev_b32_e32 v20, 16, v242
	v_and_b32_e32 v21, 0xffff0000, v242
	v_lshlrev_b32_e32 v22, 16, v243
	v_and_b32_e32 v23, 0xffff0000, v243
	v_mul_f32_e32 v5, 0xbfb8aa3b, v20
	v_mul_f32_e32 v24, 0xbfb8aa3b, v21
	v_mul_f32_e32 v25, 0xbfb8aa3b, v22
	v_mul_f32_e32 v26, 0xbfb8aa3b, v23
	v_exp_f32_e32 v5, v5
	v_exp_f32_e32 v24, v24
	v_exp_f32_e32 v25, v25
	v_exp_f32_e32 v26, v26
	v_add_f32_e32 v5, 1.0, v5
	v_add_f32_e32 v27, 1.0, v24
	v_add_f32_e32 v28, 1.0, v25
	v_add_f32_e32 v29, 1.0, v26
	v_rcp_f32_e32 v24, v5
	v_rcp_f32_e32 v25, v27
	v_rcp_f32_e32 v26, v28
	v_rcp_f32_e32 v27, v29
	v_mul_f32_e32 v16, v16, v4
	v_mul_f32_e32 v17, v17, v4
	v_mul_f32_e32 v6, v6, v4
	v_mul_f32_e32 v7, v7, v4
	v_mul_f32_e32 v20, v24, v20
	v_mul_f32_e32 v21, v25, v21
	v_mul_f32_e32 v22, v26, v22
	v_mul_f32_e32 v23, v27, v23
	s_waitcnt lgkmcnt(0)
	v_mul_f32_e32 v8, v16, v8
	v_mul_f32_e32 v9, v17, v9
	v_mul_f32_e32 v6, v6, v10
	v_mul_f32_e32 v7, v7, v11
	v_mul_f32_e32 v8, v8, v20
	v_mul_f32_e32 v9, v9, v21
	v_mul_f32_e32 v6, v6, v22
	v_mul_f32_e32 v7, v7, v23
	v_cvt_pk_bf16_f32 v8, v8, v9
	v_cvt_pk_bf16_f32 v9, v6, v7
	ds_write_b64 v250, v[8:9] offset:208
	ds_read_b128 v[6:9], v144 offset:448
	v_lshlrev_b32_e32 v10, 16, v244
	v_and_b32_e32 v11, 0xffff0000, v244
	v_lshlrev_b32_e32 v16, 16, v245
	v_and_b32_e32 v17, 0xffff0000, v245
	v_mul_f32_e32 v5, 0xbfb8aa3b, v10
	v_mul_f32_e32 v18, 0xbfb8aa3b, v11
	v_mul_f32_e32 v19, 0xbfb8aa3b, v16
	v_mul_f32_e32 v20, 0xbfb8aa3b, v17
	v_exp_f32_e32 v5, v5
	v_exp_f32_e32 v18, v18
	v_exp_f32_e32 v19, v19
	v_exp_f32_e32 v20, v20
	v_add_f32_e32 v5, 1.0, v5
	v_add_f32_e32 v21, 1.0, v18
	v_add_f32_e32 v22, 1.0, v19
	v_add_f32_e32 v23, 1.0, v20
	v_rcp_f32_e32 v18, v5
	v_rcp_f32_e32 v19, v21
	v_rcp_f32_e32 v20, v22
	v_rcp_f32_e32 v21, v23
	v_mul_f32_e32 v2, v2, v4
	v_mul_f32_e32 v3, v3, v4
	v_mul_f32_e32 v0, v0, v4
	v_mul_f32_e32 v1, v1, v4
	v_mul_f32_e32 v10, v18, v10
	v_mul_f32_e32 v11, v19, v11
	v_mul_f32_e32 v16, v20, v16
	v_mul_f32_e32 v17, v21, v17
	s_waitcnt lgkmcnt(0)
	v_mul_f32_e32 v2, v2, v6
	v_mul_f32_e32 v3, v3, v7
	v_mul_f32_e32 v0, v0, v8
	v_mul_f32_e32 v1, v1, v9
	v_mul_f32_e32 v2, v2, v10
	v_mul_f32_e32 v3, v3, v11
	v_mul_f32_e32 v0, v0, v16
	v_mul_f32_e32 v1, v1, v17
	v_cvt_pk_bf16_f32 v2, v2, v3
	v_cvt_pk_bf16_f32 v3, v0, v1
	ds_write_b64 v250, v[2:3] offset:224
	ds_read_b128 v[0:3], v144 offset:480
	v_lshlrev_b32_e32 v6, 16, v218
	v_and_b32_e32 v7, 0xffff0000, v218
	v_lshlrev_b32_e32 v8, 16, v219
	v_and_b32_e32 v9, 0xffff0000, v219
	v_mul_f32_e32 v5, 0xbfb8aa3b, v6
	v_mul_f32_e32 v10, 0xbfb8aa3b, v7
	v_mul_f32_e32 v11, 0xbfb8aa3b, v8
	v_mul_f32_e32 v16, 0xbfb8aa3b, v9
	v_exp_f32_e32 v5, v5
	v_exp_f32_e32 v10, v10
	v_exp_f32_e32 v11, v11
	v_exp_f32_e32 v16, v16
	v_add_f32_e32 v5, 1.0, v5
	v_add_f32_e32 v17, 1.0, v10
	v_add_f32_e32 v18, 1.0, v11
	v_add_f32_e32 v19, 1.0, v16
	v_rcp_f32_e32 v10, v5
	v_rcp_f32_e32 v11, v17
	v_rcp_f32_e32 v16, v18
	v_rcp_f32_e32 v17, v19
	v_mul_f32_e32 v12, v12, v4
	v_mul_f32_e32 v13, v13, v4
	v_mul_f32_e32 v5, v15, v4
	v_mul_f32_e32 v4, v14, v4
	v_mul_f32_e32 v6, v10, v6
	v_mul_f32_e32 v7, v11, v7
	v_mul_f32_e32 v8, v16, v8
	v_mul_f32_e32 v9, v17, v9
	s_waitcnt lgkmcnt(0)
	v_mul_f32_e32 v0, v12, v0
	v_mul_f32_e32 v1, v13, v1
	v_mul_f32_e32 v2, v4, v2
	v_mul_f32_e32 v3, v5, v3
	v_mul_f32_e32 v0, v0, v6
	v_mul_f32_e32 v1, v1, v7
	v_mul_f32_e32 v2, v2, v8
	v_mul_f32_e32 v3, v3, v9
	v_cvt_pk_bf16_f32 v0, v0, v1
	v_cvt_pk_bf16_f32 v1, v2, v3
	ds_write_b64 v250, v[0:1] offset:240
	s_waitcnt lgkmcnt(0)
	ds_read_b64 v[214:215], v249
	ds_read_b64 v[216:217], v249 offset:528
	ds_read_b64 v[218:219], v249 offset:1056
	ds_read_b64 v[220:221], v249 offset:1584
	ds_read_b64 v[222:223], v249 offset:2112
	ds_read_b64 v[224:225], v249 offset:2640
	ds_read_b64 v[226:227], v249 offset:3168
	ds_read_b64 v[228:229], v249 offset:3696
	ds_read_b64 v[230:231], v249 offset:4224
	ds_read_b64 v[232:233], v249 offset:4752
	ds_read_b64 v[234:235], v249 offset:5280
	ds_read_b64 v[236:237], v249 offset:5808
	ds_read_b64 v[238:239], v249 offset:6336
	ds_read_b64 v[240:241], v249 offset:6864
	ds_read_b64 v[242:243], v249 offset:7392
	ds_read_b64 v[244:245], v249 offset:7920
	s_sub_u32 s12, s12, 0x40000
	s_subb_u32 s13, s13, 0
	s_waitcnt lgkmcnt(0)
	global_store_dwordx2 v248, v[214:215], s[12:13]
	s_add_u32 s12, s12, 0x4000
	s_addc_u32 s13, s13, 0
	global_store_dwordx2 v248, v[216:217], s[12:13]
	s_add_u32 s12, s12, 0x4000
	s_addc_u32 s13, s13, 0
	global_store_dwordx2 v248, v[218:219], s[12:13]
	s_add_u32 s12, s12, 0x4000
	s_addc_u32 s13, s13, 0
	global_store_dwordx2 v248, v[220:221], s[12:13]
	s_add_u32 s12, s12, 0x4000
	s_addc_u32 s13, s13, 0
	global_store_dwordx2 v248, v[222:223], s[12:13]
	s_add_u32 s12, s12, 0x4000
	s_addc_u32 s13, s13, 0
	global_store_dwordx2 v248, v[224:225], s[12:13]
	s_add_u32 s12, s12, 0x4000
	s_addc_u32 s13, s13, 0
	global_store_dwordx2 v248, v[226:227], s[12:13]
	s_add_u32 s12, s12, 0x4000
	s_addc_u32 s13, s13, 0
	global_store_dwordx2 v248, v[228:229], s[12:13]
	s_add_u32 s12, s12, 0x4000
	s_addc_u32 s13, s13, 0
	global_store_dwordx2 v248, v[230:231], s[12:13]
	s_add_u32 s12, s12, 0x4000
	s_addc_u32 s13, s13, 0
	global_store_dwordx2 v248, v[232:233], s[12:13]
	s_add_u32 s12, s12, 0x4000
	s_addc_u32 s13, s13, 0
	global_store_dwordx2 v248, v[234:235], s[12:13]
	s_add_u32 s12, s12, 0x4000
	s_addc_u32 s13, s13, 0
	global_store_dwordx2 v248, v[236:237], s[12:13]
	s_add_u32 s12, s12, 0x4000
	s_addc_u32 s13, s13, 0
	global_store_dwordx2 v248, v[238:239], s[12:13]
	s_add_u32 s12, s12, 0x4000
	s_addc_u32 s13, s13, 0
	global_store_dwordx2 v248, v[240:241], s[12:13]
	s_add_u32 s12, s12, 0x4000
	s_addc_u32 s13, s13, 0
	global_store_dwordx2 v248, v[242:243], s[12:13]
	s_add_u32 s12, s12, 0x4000
	s_addc_u32 s13, s13, 0
	global_store_dwordx2 v248, v[244:245], s[12:13]
	s_add_u32 s12, s12, 0x4000
	s_addc_u32 s13, s13, 0
	s_branch .LBB0_229
